# v44: v37 + in-proj K-loop back-edge rotation (7.11): next iteration's scalar address chain in the shadow of the last MFMA section, fast re-entry at the first LDS reads
# speedup vs baseline: 1.0227x; 1.0085x over previous
; #define G_STAGE(bufoff, gbase, voff) do { _Pragma("unroll") for (int _i = 0; _i < 2; ++_i) \
;     __builtin_amdgcn_global_load_lds((const unsigned*)((const char*)(gbase) + (voff)[_i]), (LAS unsigned*)(lds + (bufoff) + ldsw + _i * 8192), 16, 0, 0); } while (0)
; #define G_LDA(dst, b, h) do { _Pragma("unroll") for (int m = 0; m < 4; ++m) _Pragma("unroll") for (int k = 0; k < 2; ++k) dst[m][k] = *(const LAS bf16x8*)(lds + G_SA(b, h) + aoff + m * 2048 + k * 1024); } while (0)
; #define G_LDB(dst, b, h) do { _Pragma("unroll") for (int n = 0; n < 2; ++n) _Pragma("unroll") for (int k = 0; k < 2; ++k) dst[n][k] = *(const LAS bf16x8*)(lds + G_SB(b, h) + boff + n * 2048 + k * 1024); } while (0)
; #define G_MMA(ai, bj, At, Bt) do { __builtin_amdgcn_s_setprio(1); _Pragma("unroll") for (int m = 0; m < 4; ++m) _Pragma("unroll") for (int n = 0; n < 2; ++n) _Pragma("unroll") for (int k = 0; k < 2; ++k) \
;     acc[ai][bj][m][n] = __builtin_amdgcn_mfma_f32_16x16x32_bf16(Bt[n][k], At[m][k], acc[ai][bj][m][n], 0, 0, 0); __builtin_amdgcn_s_setprio(0); } while (0)
; #define G_WAIT_V(n) asm volatile("s_waitcnt vmcnt(" #n ")" ::: "memory")
; #define G_WAIT_L(n) asm volatile("s_waitcnt lgkmcnt(" #n ")" ::: "memory")
; #define G_BAR __builtin_amdgcn_s_barrier()
; #define G_SCHED __builtin_amdgcn_sched_barrier(0)
; template <int GP> DI void gemm_phase(const Params& p, int l, int which, char* smem, int wv) {
;     ...
;     for (int t = 0; t < cnk; t += 2) {
;       const bool last = (t == cnk - 2);
;       const char* a1 = cA + (size_t)(t + 1) * kstep;
;       const char* a2 = last ? nA : cA + (size_t)(t + 2) * kstep; const char* b2 = last ? nB : cB + (size_t)(t + 2) * kstep;
;       const char* a3 = a2 + kstep; const char* b3 = b2 + kstep;
;       if (last) {
; #pragma unroll
;         for (int i = 0; i < 2; ++i) { vb0[i] = voffB(i, 0, n32); vb1[i] = voffB(i, 1, n32); }
;       }
;       G_LDB(B0, 0, 0); G_SCHED; G_LDA(At, 0, 0); G_STAGE(G_SA(1, 1), a1 + hstep, voffA);
;       G_WAIT_L(8); G_BAR; G_WAIT_L(0); G_MMA(0, 0, At, B0); G_BAR; G_SCHED;
;       G_LDB(B1, 0, 1); G_STAGE(G_SB(0, 0), b2, vb0);
;       G_BAR; G_WAIT_L(0); G_MMA(0, 1, At, B1); G_BAR;
;       G_LDA(At, 0, 1); G_STAGE(G_SA(0, 0), a2, voffA);
;       G_BAR; G_WAIT_L(0); G_MMA(1, 0, At, B0); G_BAR; G_SCHED;
;       G_STAGE(G_SB(0, 1), b2, vb1);
;       G_WAIT_V(6); G_BAR; G_MMA(1, 1, At, B1); G_BAR;
.LBB0_209:
	s_add_u32 s8, s28, s2
	v_add_u32_e32 v228, 0x10000, v212
	s_addc_u32 s9, s29, s3
	s_add_u32 s100, s8, 0x80080
	s_addc_u32 s101, s9, 0
	s_add_u32 s52, s8, 0x100
	s_addc_u32 s53, s9, 0
	s_and_b64 s[8:9], s[6:7], exec
	s_cselect_b32 s9, s10, s53
	s_cselect_b32 s8, s11, s52
	s_add_u32 s52, s74, s2
	s_addc_u32 s53, s75, s3
	s_and_b64 s[6:7], s[6:7], exec
	s_cselect_b32 s7, s37, s53
	s_cselect_b32 s6, s39, s52
.Lkf_top:
	ds_read_b128 v[148:151], v228
	ds_read_b128 v[152:155], v228 offset:1024
	ds_read_b128 v[156:159], v228 offset:2048
	ds_read_b128 v[160:163], v228 offset:3072
	s_add_i32 m0, s23, 0xc000
	ds_read_b128 v[164:167], v211
	ds_read_b128 v[168:171], v211 offset:1024
	ds_read_b128 v[172:175], v211 offset:2048
	ds_read_b128 v[176:179], v211 offset:3072
	ds_read_b128 v[180:183], v211 offset:4096
	ds_read_b128 v[184:187], v211 offset:5120
	ds_read_b128 v[188:191], v211 offset:6144
	ds_read_b128 v[192:195], v211 offset:7168
	global_load_lds_dwordx4 v138, s[100:101]
	s_add_i32 m0, s23, 0xe000
	s_nop 0
	global_load_lds_dwordx4 v140, s[100:101]
	s_waitcnt lgkmcnt(8)
	s_barrier
	s_waitcnt lgkmcnt(0)
	s_waitcnt lgkmcnt(0)
	v_mfma_f32_16x16x32_bf16 v[62:65], v[148:151], v[164:167], v[62:65]
	v_mfma_f32_16x16x32_bf16 v[58:61], v[156:159], v[164:167], v[58:61]
	v_mfma_f32_16x16x32_bf16 v[54:57], v[148:151], v[172:175], v[54:57]
	v_mfma_f32_16x16x32_bf16 v[50:53], v[156:159], v[172:175], v[50:53]
	v_mfma_f32_16x16x32_bf16 v[46:49], v[148:151], v[180:183], v[46:49]
	v_mfma_f32_16x16x32_bf16 v[42:45], v[156:159], v[180:183], v[42:45]
	v_mfma_f32_16x16x32_bf16 v[38:41], v[148:151], v[188:191], v[38:41]
	v_mfma_f32_16x16x32_bf16 v[34:37], v[156:159], v[188:191], v[34:37]
	v_mfma_f32_16x16x32_bf16 v[62:65], v[152:155], v[168:171], v[62:65]
	v_mfma_f32_16x16x32_bf16 v[58:61], v[160:163], v[168:171], v[58:61]
	v_mfma_f32_16x16x32_bf16 v[54:57], v[152:155], v[176:179], v[54:57]
	v_mfma_f32_16x16x32_bf16 v[50:53], v[160:163], v[176:179], v[50:53]
	v_mfma_f32_16x16x32_bf16 v[46:49], v[152:155], v[184:187], v[46:49]
	v_mfma_f32_16x16x32_bf16 v[42:45], v[160:163], v[184:187], v[42:45]
	v_mfma_f32_16x16x32_bf16 v[38:41], v[152:155], v[192:195], v[38:41]
	v_mfma_f32_16x16x32_bf16 v[34:37], v[160:163], v[192:195], v[34:37]
	s_barrier
	s_mov_b32 m0, s25
	ds_read_b128 v[196:199], v228 offset:16384
	ds_read_b128 v[200:203], v228 offset:17408
	ds_read_b128 v[204:207], v228 offset:18432
	ds_read_b128 v[238:241], v228 offset:19456
	global_load_lds_dwordx4 v0, s[6:7]
	s_mov_b32 m0, s58
	s_nop 0
	global_load_lds_dwordx4 v136, s[6:7]
	s_barrier
	s_waitcnt lgkmcnt(0)
	s_waitcnt lgkmcnt(0)
	v_mfma_f32_16x16x32_bf16 v[30:33], v[196:199], v[164:167], v[30:33]
	v_mfma_f32_16x16x32_bf16 v[26:29], v[204:207], v[164:167], v[26:29]
	v_mfma_f32_16x16x32_bf16 v[22:25], v[196:199], v[172:175], v[22:25]
	v_mfma_f32_16x16x32_bf16 v[18:21], v[204:207], v[172:175], v[18:21]
	v_mfma_f32_16x16x32_bf16 v[14:17], v[196:199], v[180:183], v[14:17]
	v_mfma_f32_16x16x32_bf16 v[10:13], v[204:207], v[180:183], v[10:13]
	v_mfma_f32_16x16x32_bf16 v[6:9], v[196:199], v[188:191], v[6:9]
	v_mfma_f32_16x16x32_bf16 v[2:5], v[204:207], v[188:191], v[2:5]
	v_mfma_f32_16x16x32_bf16 v[30:33], v[200:203], v[168:171], v[30:33]
	v_mfma_f32_16x16x32_bf16 v[26:29], v[238:241], v[168:171], v[26:29]
	v_mfma_f32_16x16x32_bf16 v[22:25], v[200:203], v[176:179], v[22:25]
	v_mfma_f32_16x16x32_bf16 v[18:21], v[238:241], v[176:179], v[18:21]
	v_mfma_f32_16x16x32_bf16 v[14:17], v[200:203], v[184:187], v[14:17]
	v_mfma_f32_16x16x32_bf16 v[10:13], v[238:241], v[184:187], v[10:13]
	v_mfma_f32_16x16x32_bf16 v[6:9], v[200:203], v[192:195], v[6:9]
	v_mfma_f32_16x16x32_bf16 v[2:5], v[238:241], v[192:195], v[2:5]
	s_mov_b32 m0, s23
	s_barrier
	ds_read_b128 v[164:167], v211 offset:16384
	ds_read_b128 v[168:171], v211 offset:17408
	ds_read_b128 v[172:175], v211 offset:18432
	ds_read_b128 v[176:179], v211 offset:19456
	ds_read_b128 v[180:183], v211 offset:20480
	ds_read_b128 v[184:187], v211 offset:21504
	ds_read_b128 v[188:191], v211 offset:22528
	ds_read_b128 v[192:195], v211 offset:23552
	global_load_lds_dwordx4 v132, s[8:9]
	s_mov_b32 m0, s59
	s_nop 0
	global_load_lds_dwordx4 v134, s[8:9]
	s_barrier
	s_waitcnt lgkmcnt(0)
	s_waitcnt lgkmcnt(0)
	v_mfma_f32_16x16x32_bf16 v[66:69], v[148:151], v[164:167], v[66:69]
	v_mfma_f32_16x16x32_bf16 v[70:73], v[156:159], v[164:167], v[70:73]
	v_mfma_f32_16x16x32_bf16 v[74:77], v[148:151], v[172:175], v[74:77]
	v_mfma_f32_16x16x32_bf16 v[78:81], v[156:159], v[172:175], v[78:81]
	v_mfma_f32_16x16x32_bf16 v[82:85], v[148:151], v[180:183], v[82:85]
	v_mfma_f32_16x16x32_bf16 v[86:89], v[156:159], v[180:183], v[86:89]
	v_mfma_f32_16x16x32_bf16 v[90:93], v[148:151], v[188:191], v[90:93]
	v_mfma_f32_16x16x32_bf16 v[94:97], v[156:159], v[188:191], v[94:97]
	v_mfma_f32_16x16x32_bf16 v[66:69], v[152:155], v[168:171], v[66:69]
	v_mfma_f32_16x16x32_bf16 v[70:73], v[160:163], v[168:171], v[70:73]
	v_mfma_f32_16x16x32_bf16 v[74:77], v[152:155], v[176:179], v[74:77]
	v_mfma_f32_16x16x32_bf16 v[78:81], v[160:163], v[176:179], v[78:81]
	v_mfma_f32_16x16x32_bf16 v[82:85], v[152:155], v[184:187], v[82:85]
	v_mfma_f32_16x16x32_bf16 v[86:89], v[160:163], v[184:187], v[86:89]
	v_mfma_f32_16x16x32_bf16 v[90:93], v[152:155], v[192:195], v[90:93]
	v_mfma_f32_16x16x32_bf16 v[94:97], v[160:163], v[192:195], v[94:97]
	s_barrier
	s_mov_b32 m0, s60
	s_nop 0
	global_load_lds_dwordx4 v130, s[6:7]
	s_mov_b32 m0, s61
	s_nop 0
	global_load_lds_dwordx4 v142, s[6:7]
	s_waitcnt vmcnt(6)
	s_barrier
; #define G_STAGE(bufoff, gbase, voff) do { _Pragma("unroll") for (int _i = 0; _i < 2; ++_i) \
;     __builtin_amdgcn_global_load_lds((const unsigned*)((const char*)(gbase) + (voff)[_i]), (LAS unsigned*)(lds + (bufoff) + ldsw + _i * 8192), 16, 0, 0); } while (0)
; #define G_LDA(dst, b, h) do { _Pragma("unroll") for (int m = 0; m < 4; ++m) _Pragma("unroll") for (int k = 0; k < 2; ++k) dst[m][k] = *(const LAS bf16x8*)(lds + G_SA(b, h) + aoff + m * 2048 + k * 1024); } while (0)
; #define G_LDB(dst, b, h) do { _Pragma("unroll") for (int n = 0; n < 2; ++n) _Pragma("unroll") for (int k = 0; k < 2; ++k) dst[n][k] = *(const LAS bf16x8*)(lds + G_SB(b, h) + boff + n * 2048 + k * 1024); } while (0)
; #define G_MMA(ai, bj, At, Bt) do { __builtin_amdgcn_s_setprio(1); _Pragma("unroll") for (int m = 0; m < 4; ++m) _Pragma("unroll") for (int n = 0; n < 2; ++n) _Pragma("unroll") for (int k = 0; k < 2; ++k) \
;     acc[ai][bj][m][n] = __builtin_amdgcn_mfma_f32_16x16x32_bf16(Bt[n][k], At[m][k], acc[ai][bj][m][n], 0, 0, 0); __builtin_amdgcn_s_setprio(0); } while (0)
; #define G_WAIT_V(n) asm volatile("s_waitcnt vmcnt(" #n ")" ::: "memory")
; #define G_WAIT_L(n) asm volatile("s_waitcnt lgkmcnt(" #n ")" ::: "memory")
; #define G_BAR __builtin_amdgcn_s_barrier()
; #define G_SCHED __builtin_amdgcn_sched_barrier(0)
; template <int GP> DI void gemm_phase(const Params& p, int l, int which, char* smem, int wv) {
;     ...
;       G_WAIT_V(6); G_BAR; G_MMA(1, 1, At, B1); G_BAR;
;       G_LDB(B0, 1, 0); G_SCHED; G_LDA(At, 1, 0); G_STAGE(G_SA(0, 1), a2 + hstep, voffA);
;       G_WAIT_L(8); G_BAR; G_WAIT_L(0); G_MMA(0, 0, At, B0); G_BAR; G_SCHED;
;       G_LDB(B1, 1, 1); G_STAGE(G_SB(1, 0), b3, vb0);
;       G_BAR; G_WAIT_L(0); G_MMA(0, 1, At, B1); G_BAR;
;       G_LDA(At, 1, 1); G_STAGE(G_SA(1, 0), a3, voffA);
	v_mfma_f32_16x16x32_bf16 v[98:101], v[196:199], v[164:167], v[98:101]
	v_mfma_f32_16x16x32_bf16 v[102:105], v[204:207], v[164:167], v[102:105]
	v_mfma_f32_16x16x32_bf16 v[106:109], v[196:199], v[172:175], v[106:109]
	v_mfma_f32_16x16x32_bf16 v[110:113], v[204:207], v[172:175], v[110:113]
	v_mfma_f32_16x16x32_bf16 v[114:117], v[196:199], v[180:183], v[114:117]
	v_mfma_f32_16x16x32_bf16 v[118:121], v[204:207], v[180:183], v[118:121]
	v_mfma_f32_16x16x32_bf16 v[122:125], v[196:199], v[188:191], v[122:125]
	v_mfma_f32_16x16x32_bf16 v[126:129], v[204:207], v[188:191], v[126:129]
	v_mfma_f32_16x16x32_bf16 v[98:101], v[200:203], v[168:171], v[98:101]
	v_mfma_f32_16x16x32_bf16 v[102:105], v[238:241], v[168:171], v[102:105]
	v_mfma_f32_16x16x32_bf16 v[106:109], v[200:203], v[176:179], v[106:109]
	v_mfma_f32_16x16x32_bf16 v[110:113], v[238:241], v[176:179], v[110:113]
	v_mfma_f32_16x16x32_bf16 v[114:117], v[200:203], v[184:187], v[114:117]
	v_mfma_f32_16x16x32_bf16 v[118:121], v[238:241], v[184:187], v[118:121]
	v_mfma_f32_16x16x32_bf16 v[122:125], v[200:203], v[192:195], v[122:125]
	v_mfma_f32_16x16x32_bf16 v[126:129], v[238:241], v[192:195], v[126:129]
	s_barrier
	ds_read_b128 v[148:151], v228 offset:32768
	ds_read_b128 v[152:155], v228 offset:33792
	ds_read_b128 v[156:159], v228 offset:34816
	ds_read_b128 v[160:163], v228 offset:35840
	s_add_u32 s100, s8, 0x80000
	s_addc_u32 s101, s9, 0
	s_mov_b32 m0, s62
	ds_read_b128 v[164:167], v211 offset:32768
	ds_read_b128 v[168:171], v211 offset:33792
	ds_read_b128 v[172:175], v211 offset:34816
	ds_read_b128 v[176:179], v211 offset:35840
	ds_read_b128 v[180:183], v211 offset:36864
	ds_read_b128 v[184:187], v211 offset:37888
	ds_read_b128 v[188:191], v211 offset:38912
	ds_read_b128 v[192:195], v211 offset:39936
	global_load_lds_dwordx4 v132, s[100:101]
	s_mov_b32 m0, s63
	s_nop 0
	global_load_lds_dwordx4 v134, s[100:101]
	s_waitcnt lgkmcnt(8)
	s_barrier
	s_waitcnt lgkmcnt(0)
	s_waitcnt lgkmcnt(0)
	v_mfma_f32_16x16x32_bf16 v[62:65], v[148:151], v[164:167], v[62:65]
	v_mfma_f32_16x16x32_bf16 v[58:61], v[156:159], v[164:167], v[58:61]
	v_mfma_f32_16x16x32_bf16 v[54:57], v[148:151], v[172:175], v[54:57]
	v_mfma_f32_16x16x32_bf16 v[50:53], v[156:159], v[172:175], v[50:53]
	v_mfma_f32_16x16x32_bf16 v[46:49], v[148:151], v[180:183], v[46:49]
	v_mfma_f32_16x16x32_bf16 v[42:45], v[156:159], v[180:183], v[42:45]
	v_mfma_f32_16x16x32_bf16 v[38:41], v[148:151], v[188:191], v[38:41]
	v_mfma_f32_16x16x32_bf16 v[34:37], v[156:159], v[188:191], v[34:37]
	v_mfma_f32_16x16x32_bf16 v[62:65], v[152:155], v[168:171], v[62:65]
	v_mfma_f32_16x16x32_bf16 v[58:61], v[160:163], v[168:171], v[58:61]
	v_mfma_f32_16x16x32_bf16 v[54:57], v[152:155], v[176:179], v[54:57]
	v_mfma_f32_16x16x32_bf16 v[50:53], v[160:163], v[176:179], v[50:53]
	v_mfma_f32_16x16x32_bf16 v[46:49], v[152:155], v[184:187], v[46:49]
	v_mfma_f32_16x16x32_bf16 v[42:45], v[160:163], v[184:187], v[42:45]
	v_mfma_f32_16x16x32_bf16 v[38:41], v[152:155], v[192:195], v[38:41]
	v_mfma_f32_16x16x32_bf16 v[34:37], v[160:163], v[192:195], v[34:37]
	s_barrier
	s_mov_b32 m0, s21
	s_add_u32 s100, s6, s16
	s_addc_u32 s101, s7, s17
	ds_read_b128 v[196:199], v228 offset:49152
	ds_read_b128 v[200:203], v228 offset:50176
	ds_read_b128 v[204:207], v228 offset:51200
	ds_read_b128 v[238:241], v228 offset:52224
	global_load_lds_dwordx4 v0, s[100:101]
	s_mov_b32 m0, s64
	s_nop 0
	global_load_lds_dwordx4 v136, s[100:101]
	s_barrier
; #define G_STAGE(bufoff, gbase, voff) do { _Pragma("unroll") for (int _i = 0; _i < 2; ++_i) \
;     __builtin_amdgcn_global_load_lds((const unsigned*)((const char*)(gbase) + (voff)[_i]), (LAS unsigned*)(lds + (bufoff) + ldsw + _i * 8192), 16, 0, 0); } while (0)
; #define G_LDA(dst, b, h) do { _Pragma("unroll") for (int m = 0; m < 4; ++m) _Pragma("unroll") for (int k = 0; k < 2; ++k) dst[m][k] = *(const LAS bf16x8*)(lds + G_SA(b, h) + aoff + m * 2048 + k * 1024); } while (0)
; #define G_LDB(dst, b, h) do { _Pragma("unroll") for (int n = 0; n < 2; ++n) _Pragma("unroll") for (int k = 0; k < 2; ++k) dst[n][k] = *(const LAS bf16x8*)(lds + G_SB(b, h) + boff + n * 2048 + k * 1024); } while (0)
; #define G_MMA(ai, bj, At, Bt) do { __builtin_amdgcn_s_setprio(1); _Pragma("unroll") for (int m = 0; m < 4; ++m) _Pragma("unroll") for (int n = 0; n < 2; ++n) _Pragma("unroll") for (int k = 0; k < 2; ++k) \
;     acc[ai][bj][m][n] = __builtin_amdgcn_mfma_f32_16x16x32_bf16(Bt[n][k], At[m][k], acc[ai][bj][m][n], 0, 0, 0); __builtin_amdgcn_s_setprio(0); } while (0)
; #define G_WAIT_V(n) asm volatile("s_waitcnt vmcnt(" #n ")" ::: "memory")
; #define G_WAIT_L(n) asm volatile("s_waitcnt lgkmcnt(" #n ")" ::: "memory")
; #define G_BAR __builtin_amdgcn_s_barrier()
; #define G_SCHED __builtin_amdgcn_sched_barrier(0)
; template <int GP> DI void gemm_phase(const Params& p, int l, int which, char* smem, int wv) {
;     ...
;     for (int t = 0; t < cnk; t += 2) {
;       const bool last = (t == cnk - 2);
;       const char* a1 = cA + (size_t)(t + 1) * kstep;
;       const char* a2 = last ? nA : cA + (size_t)(t + 2) * kstep; const char* b2 = last ? nB : cB + (size_t)(t + 2) * kstep;
;     ...
;       G_WAIT_V(6); G_BAR; G_MMA(1, 1, At, B1); G_BAR;
;       G_LDB(B0, 1, 0); G_SCHED; G_LDA(At, 1, 0); G_STAGE(G_SA(0, 1), a2 + hstep, voffA);
;       G_WAIT_L(8); G_BAR; G_WAIT_L(0); G_MMA(0, 0, At, B0); G_BAR; G_SCHED;
;       G_LDB(B1, 1, 1); G_STAGE(G_SB(1, 0), b3, vb0);
;       G_BAR; G_WAIT_L(0); G_MMA(0, 1, At, B1); G_BAR;
;       G_LDA(At, 1, 1); G_STAGE(G_SA(1, 0), a3, voffA);
;       G_BAR; G_WAIT_L(0); G_MMA(1, 0, At, B0); G_BAR; G_SCHED;
;       G_STAGE(G_SB(1, 1), b3, vb1);
;       G_WAIT_V(6); G_BAR; G_MMA(1, 1, At, B1); G_BAR;
	s_waitcnt lgkmcnt(0)
	s_waitcnt lgkmcnt(0)
	v_mfma_f32_16x16x32_bf16 v[30:33], v[196:199], v[164:167], v[30:33]
	v_mfma_f32_16x16x32_bf16 v[26:29], v[204:207], v[164:167], v[26:29]
	v_mfma_f32_16x16x32_bf16 v[22:25], v[196:199], v[172:175], v[22:25]
	v_mfma_f32_16x16x32_bf16 v[18:21], v[204:207], v[172:175], v[18:21]
	v_mfma_f32_16x16x32_bf16 v[14:17], v[196:199], v[180:183], v[14:17]
	v_mfma_f32_16x16x32_bf16 v[10:13], v[204:207], v[180:183], v[10:13]
	v_mfma_f32_16x16x32_bf16 v[6:9], v[196:199], v[188:191], v[6:9]
	v_mfma_f32_16x16x32_bf16 v[2:5], v[204:207], v[188:191], v[2:5]
	v_mfma_f32_16x16x32_bf16 v[30:33], v[200:203], v[168:171], v[30:33]
	v_mfma_f32_16x16x32_bf16 v[26:29], v[238:241], v[168:171], v[26:29]
	v_mfma_f32_16x16x32_bf16 v[22:25], v[200:203], v[176:179], v[22:25]
	v_mfma_f32_16x16x32_bf16 v[18:21], v[238:241], v[176:179], v[18:21]
	v_mfma_f32_16x16x32_bf16 v[14:17], v[200:203], v[184:187], v[14:17]
	v_mfma_f32_16x16x32_bf16 v[10:13], v[238:241], v[184:187], v[10:13]
	v_mfma_f32_16x16x32_bf16 v[6:9], v[200:203], v[192:195], v[6:9]
	v_mfma_f32_16x16x32_bf16 v[2:5], v[238:241], v[192:195], v[2:5]
	s_mov_b32 m0, s65
	s_add_u32 s100, s8, s16
	s_addc_u32 s101, s9, s17
	s_barrier
	ds_read_b128 v[164:167], v211 offset:49152
	ds_read_b128 v[168:171], v211 offset:50176
	ds_read_b128 v[172:175], v211 offset:51200
	ds_read_b128 v[176:179], v211 offset:52224
	ds_read_b128 v[180:183], v211 offset:53248
	ds_read_b128 v[184:187], v211 offset:54272
	ds_read_b128 v[188:191], v211 offset:55296
	ds_read_b128 v[192:195], v211 offset:56320
	global_load_lds_dwordx4 v132, s[100:101]
	s_mov_b32 m0, s66
	s_nop 0
	global_load_lds_dwordx4 v134, s[100:101]
	s_barrier
	s_waitcnt lgkmcnt(0)
	s_waitcnt lgkmcnt(0)
	v_mfma_f32_16x16x32_bf16 v[66:69], v[148:151], v[164:167], v[66:69]
	v_mfma_f32_16x16x32_bf16 v[70:73], v[156:159], v[164:167], v[70:73]
	v_mfma_f32_16x16x32_bf16 v[74:77], v[148:151], v[172:175], v[74:77]
	v_mfma_f32_16x16x32_bf16 v[78:81], v[156:159], v[172:175], v[78:81]
	v_mfma_f32_16x16x32_bf16 v[82:85], v[148:151], v[180:183], v[82:85]
	v_mfma_f32_16x16x32_bf16 v[86:89], v[156:159], v[180:183], v[86:89]
	v_mfma_f32_16x16x32_bf16 v[90:93], v[148:151], v[188:191], v[90:93]
	v_mfma_f32_16x16x32_bf16 v[94:97], v[156:159], v[188:191], v[94:97]
	v_mfma_f32_16x16x32_bf16 v[66:69], v[152:155], v[168:171], v[66:69]
	v_mfma_f32_16x16x32_bf16 v[70:73], v[160:163], v[168:171], v[70:73]
	v_mfma_f32_16x16x32_bf16 v[74:77], v[152:155], v[176:179], v[74:77]
	v_mfma_f32_16x16x32_bf16 v[78:81], v[160:163], v[176:179], v[78:81]
	v_mfma_f32_16x16x32_bf16 v[82:85], v[152:155], v[184:187], v[82:85]
	v_mfma_f32_16x16x32_bf16 v[86:89], v[160:163], v[184:187], v[86:89]
	v_mfma_f32_16x16x32_bf16 v[90:93], v[152:155], v[192:195], v[90:93]
	v_mfma_f32_16x16x32_bf16 v[94:97], v[160:163], v[192:195], v[94:97]
	s_barrier
	s_mov_b32 m0, s67
	s_add_u32 s100, s6, s16
	s_addc_u32 s101, s7, s17
	global_load_lds_dwordx4 v130, s[100:101]
	s_mov_b32 m0, s68
	s_nop 0
	global_load_lds_dwordx4 v142, s[100:101]
	s_waitcnt vmcnt(6)
	s_barrier
	v_mfma_f32_16x16x32_bf16 v[98:101], v[196:199], v[164:167], v[98:101]
	v_mfma_f32_16x16x32_bf16 v[102:105], v[204:207], v[164:167], v[102:105]
	v_mfma_f32_16x16x32_bf16 v[106:109], v[196:199], v[172:175], v[106:109]
	v_mfma_f32_16x16x32_bf16 v[110:113], v[204:207], v[172:175], v[110:113]
	v_mfma_f32_16x16x32_bf16 v[114:117], v[196:199], v[180:183], v[114:117]
	v_mfma_f32_16x16x32_bf16 v[118:121], v[204:207], v[180:183], v[118:121]
	v_mfma_f32_16x16x32_bf16 v[122:125], v[196:199], v[188:191], v[122:125]
	v_mfma_f32_16x16x32_bf16 v[126:129], v[204:207], v[188:191], v[126:129]
	v_mfma_f32_16x16x32_bf16 v[98:101], v[200:203], v[168:171], v[98:101]
	s_add_i32 s50, s50, 2
	s_add_u32 s2, s2, 0x100
	s_addc_u32 s3, s3, 0
	v_mfma_f32_16x16x32_bf16 v[102:105], v[238:241], v[168:171], v[102:105]
	s_add_u32 s8, s28, s2
	s_addc_u32 s9, s29, s3
	v_mfma_f32_16x16x32_bf16 v[106:109], v[200:203], v[176:179], v[106:109]
	s_add_u32 s100, s8, 0x80080
	s_addc_u32 s101, s9, 0
	v_mfma_f32_16x16x32_bf16 v[110:113], v[238:241], v[176:179], v[110:113]
	s_add_u32 s8, s8, 0x100
	s_addc_u32 s9, s9, 0
	v_mfma_f32_16x16x32_bf16 v[114:117], v[200:203], v[184:187], v[114:117]
	s_add_u32 s6, s74, s2
	s_addc_u32 s7, s75, s3
	v_mfma_f32_16x16x32_bf16 v[118:121], v[238:241], v[184:187], v[118:121]
	v_mfma_f32_16x16x32_bf16 v[122:125], v[200:203], v[192:195], v[122:125]
	v_mfma_f32_16x16x32_bf16 v[126:129], v[238:241], v[192:195], v[126:129]
	s_cmp_gt_u32 s50, 29
	s_barrier
	s_cbranch_scc1 .LBB0_219
	s_cmpk_lg_i32 s2, 0xf00
	s_cbranch_scc1 .Lkf_top
